# P5 fix-up: both residual load pairs issued together (one HBM round trip per item), on top of rotary prefetch + P5 4-slice tail
# baseline (speedup 1.0000x reference)
.LBB0_1152:
	s_or_b64 exec, exec, s[10:11]
	s_waitcnt vmcnt(14)
	v_pk_add_f32 v[66:67], v[66:67], v[70:71]
	v_pk_add_f32 v[64:65], v[64:65], v[68:69]
	s_waitcnt vmcnt(10)
	v_pk_add_f32 v[68:69], v[90:91], v[102:103]
	v_pk_add_f32 v[70:71], v[88:89], v[100:101]
	v_pk_add_f32 v[66:67], v[66:67], v[78:79]
	v_pk_add_f32 v[64:65], v[64:65], v[76:77]
	s_waitcnt vmcnt(9)
	v_pk_add_f32 v[68:69], v[68:69], v[110:111]
	v_pk_add_f32 v[70:71], v[70:71], v[108:109]
	v_pk_add_f32 v[66:67], v[66:67], v[74:75]
	v_pk_add_f32 v[64:65], v[64:65], v[72:73]
	s_waitcnt vmcnt(8)
	v_pk_add_f32 v[68:69], v[68:69], v[106:107]
	v_pk_add_f32 v[70:71], v[70:71], v[104:105]
	s_waitcnt vmcnt(8)
	s_waitcnt vmcnt(8)
	v_lshl_or_b32 v74, s0, 8, v140
	s_waitcnt vmcnt(8)
	v_mov_b32_e32 v72, v70
	v_mov_b32_e32 v73, v71
	v_ashrrev_i32_e32 v75, 31, v74
	s_waitcnt vmcnt(8)
	v_mov_b32_e32 v70, v68
	v_mov_b32_e32 v71, v69
	v_mov_b32_e32 v68, v72
	v_mov_b32_e32 v69, v73
	v_cmp_ne_u64_e32 vcc, 0, v[132:133]
	v_lshl_add_u64 v[72:73], v[74:75], 2, v[132:133]
	s_and_saveexec_b64 s[10:11], vcc
	s_cbranch_execz .LBB0_1154
	global_load_dwordx4 v[76:79], v[72:73], off nt
	global_load_dwordx4 v[80:83], v[72:73], off offset:16 nt
	global_load_dwordx4 v[232:235], v[72:73], off offset:512 nt
	global_load_dwordx4 v[236:239], v[72:73], off offset:528 nt
	s_waitcnt vmcnt(3)
	v_pk_add_f32 v[66:67], v[66:67], v[78:79]
	v_pk_add_f32 v[64:65], v[64:65], v[76:77]
	s_waitcnt vmcnt(2)
	v_pk_add_f32 v[70:71], v[70:71], v[82:83]
	v_pk_add_f32 v[68:69], v[68:69], v[80:81]
.LBB0_1154:
	s_or_b64 exec, exec, s[10:11]
	s_waitcnt vmcnt(6)
	v_pk_add_f32 v[2:3], v[2:3], v[6:7]
	v_pk_add_f32 v[0:1], v[0:1], v[4:5]
	s_waitcnt vmcnt(2)
	v_pk_add_f32 v[4:5], v[26:27], v[38:39]
	v_pk_add_f32 v[6:7], v[24:25], v[36:37]
	s_waitcnt vmcnt(1)
	v_pk_add_f32 v[4:5], v[4:5], v[46:47]
	v_pk_add_f32 v[6:7], v[6:7], v[44:45]
	v_pk_add_f32 v[2:3], v[2:3], v[14:15]
	v_pk_add_f32 v[0:1], v[0:1], v[12:13]
	s_waitcnt vmcnt(0)
	v_pk_add_f32 v[4:5], v[4:5], v[42:43]
	v_pk_add_f32 v[6:7], v[6:7], v[40:41]
	v_pk_add_f32 v[2:3], v[2:3], v[10:11]
	v_pk_add_f32 v[0:1], v[0:1], v[8:9]
	s_waitcnt vmcnt(0)
	v_ashrrev_i32_e32 v131, 31, v130
	s_waitcnt vmcnt(0)
	v_lshlrev_b64 v[76:77], 13, v[130:131]
	s_waitcnt vmcnt(0)
	v_mov_b32_e32 v8, v6
	v_mov_b32_e32 v9, v7
	s_waitcnt vmcnt(0)
	v_mov_b32_e32 v6, v4
	v_mov_b32_e32 v7, v5
	v_mov_b32_e32 v4, v8
	v_mov_b32_e32 v5, v9
	v_lshl_add_u64 v[8:9], s[8:9], 0, v[76:77]
	v_lshl_add_u64 v[8:9], v[74:75], 2, v[8:9]
	global_store_dwordx4 v[8:9], v[64:67], off
	global_store_dwordx4 v[8:9], v[68:71], off offset:16
	s_and_saveexec_b64 s[10:11], vcc
	s_cbranch_execz .LBB0_1143
	s_waitcnt vmcnt(2)
	s_nop 0
	v_pk_add_f32 v[2:3], v[2:3], v[234:235]
	v_pk_add_f32 v[0:1], v[0:1], v[232:233]
	v_pk_add_f32 v[6:7], v[6:7], v[238:239]
	v_pk_add_f32 v[4:5], v[4:5], v[236:237]
	s_branch .LBB0_1143
